# P8: half the workgroups (blockIdx bit 3) convert w_d before their quarter-height tail unit, the others after it, so the memory-bound conversion overlaps the other half's tail GEMM
# speedup vs baseline: 1.0041x; 1.0041x over previous
.LBB0_1070:
	s_bitcmp0_b32 s96, 3
	s_cbranch_scc1 .Lcvt2_done
	s_cmpk_gt_i32 s96, 0x2bf
	s_cbranch_scc1 .Lcvt2_skip
	s_mul_hi_i32 s2, s96, 0x2e8ba2e9
	v_mov_b32_e32 v50, v184
	s_lshr_b32 s3, s2, 31
	s_ashr_i32 s2, s2, 3
	s_add_i32 s2, s2, s3
	v_and_b32_e32 v2, 0x7f, v50
	s_load_dwordx2 s[6:7], s[0:1], 0xb8
	v_lshl_or_b32 v0, s2, 7, v2
	s_mul_i32 s2, s2, 44
	v_ashrrev_i32_e32 v3, 7, v50
	s_sub_i32 s2, s96, s2
	s_waitcnt vmcnt(0)
	v_lshl_add_u32 v4, s2, 7, v3
	v_ashrrev_i32_e32 v5, 31, v4
	v_lshlrev_b64 v[4:5], 13, v[4:5]
	s_waitcnt lgkmcnt(0)
	v_lshl_add_u64 v[4:5], s[6:7], 0, v[4:5]
	v_ashrrev_i32_e32 v1, 31, v0
	v_lshl_add_u64 v[0:1], v[0:1], 2, v[4:5]
	s_mov_b32 s2, 0x8000
	v_add_co_u32_e32 v12, vcc, s2, v0
	s_mov_b32 s3, 0x10000
	s_nop 0
	v_addc_co_u32_e32 v13, vcc, 0, v1, vcc
	v_add_co_u32_e32 v14, vcc, s3, v0
	s_mov_b32 s10, 0x18000
	s_nop 0
	v_addc_co_u32_e32 v15, vcc, 0, v1, vcc
	v_add_co_u32_e32 v16, vcc, s10, v0
	s_mov_b32 s11, 0x20000
	s_nop 0
	v_addc_co_u32_e32 v17, vcc, 0, v1, vcc
	v_add_co_u32_e32 v18, vcc, s11, v0
	s_mov_b32 s12, 0x28000
	s_nop 0
	v_addc_co_u32_e32 v19, vcc, 0, v1, vcc
	v_add_co_u32_e32 v20, vcc, s12, v0
	s_mov_b32 s13, 0x30000
	s_nop 0
	v_addc_co_u32_e32 v21, vcc, 0, v1, vcc
	v_add_co_u32_e32 v22, vcc, s13, v0
	s_mov_b32 s14, 0x38000
	s_nop 0
	v_addc_co_u32_e32 v23, vcc, 0, v1, vcc
	v_add_co_u32_e32 v24, vcc, s14, v0
	s_mov_b32 s15, 0x40000
	s_nop 0
	v_addc_co_u32_e32 v25, vcc, 0, v1, vcc
	global_load_dword v4, v[0:1], off nt
	global_load_dword v5, v[12:13], off nt
	global_load_dword v6, v[14:15], off nt
	global_load_dword v7, v[16:17], off nt
	global_load_dword v8, v[18:19], off nt
	global_load_dword v9, v[20:21], off nt
	global_load_dword v10, v[22:23], off nt
	global_load_dword v11, v[24:25], off nt
	v_add_co_u32_e32 v20, vcc, s15, v0
	s_mov_b32 s16, 0x48000
	s_nop 0
	v_addc_co_u32_e32 v21, vcc, 0, v1, vcc
	v_add_co_u32_e32 v22, vcc, s16, v0
	s_mov_b32 s17, 0x50000
	s_nop 0
	v_addc_co_u32_e32 v23, vcc, 0, v1, vcc
	v_add_co_u32_e32 v24, vcc, s17, v0
	s_mov_b32 s18, 0x58000
	s_nop 0
	v_addc_co_u32_e32 v25, vcc, 0, v1, vcc
	v_add_co_u32_e32 v26, vcc, s18, v0
	s_mov_b32 s19, 0x60000
	s_nop 0
	v_addc_co_u32_e32 v27, vcc, 0, v1, vcc
	v_add_co_u32_e32 v28, vcc, s19, v0
	s_mov_b32 s20, 0x68000
	s_nop 0
	v_addc_co_u32_e32 v29, vcc, 0, v1, vcc
	v_add_co_u32_e32 v30, vcc, s20, v0
	s_mov_b32 s21, 0x70000
	s_nop 0
	v_addc_co_u32_e32 v31, vcc, 0, v1, vcc
	v_add_co_u32_e32 v32, vcc, s21, v0
	s_mov_b32 s22, 0x78000
	s_nop 0
	v_addc_co_u32_e32 v33, vcc, 0, v1, vcc
	v_add_co_u32_e32 v34, vcc, s22, v0
	s_mov_b32 s23, 0x80000
	s_nop 0
	v_addc_co_u32_e32 v35, vcc, 0, v1, vcc
	global_load_dword v12, v[20:21], off nt
	global_load_dword v13, v[22:23], off nt
	global_load_dword v14, v[24:25], off nt
	global_load_dword v15, v[26:27], off nt
	global_load_dword v16, v[28:29], off nt
	global_load_dword v17, v[30:31], off nt
	global_load_dword v18, v[32:33], off nt
	global_load_dword v19, v[34:35], off nt
	v_add_co_u32_e32 v20, vcc, s23, v0
	s_mov_b32 s24, 0x88000
	s_nop 0
	v_addc_co_u32_e32 v21, vcc, 0, v1, vcc
	v_add_co_u32_e32 v22, vcc, s24, v0
	s_mov_b32 s25, 0x90000
	s_nop 0
	v_addc_co_u32_e32 v23, vcc, 0, v1, vcc
	v_add_co_u32_e32 v24, vcc, s25, v0
	s_mov_b32 s26, 0x98000
	s_nop 0
	v_addc_co_u32_e32 v25, vcc, 0, v1, vcc
	v_add_co_u32_e32 v26, vcc, s26, v0
	s_mov_b32 s27, 0xa0000
	s_nop 0
	v_addc_co_u32_e32 v27, vcc, 0, v1, vcc
	v_add_co_u32_e32 v28, vcc, s27, v0
	s_mov_b32 s28, 0xa8000
	s_nop 0
	v_addc_co_u32_e32 v29, vcc, 0, v1, vcc
	v_add_co_u32_e32 v38, vcc, s28, v0
	s_mov_b32 s29, 0xb0000
	s_nop 0
	v_addc_co_u32_e32 v39, vcc, 0, v1, vcc
	v_add_co_u32_e32 v40, vcc, s29, v0
	s_mov_b32 s30, 0xb8000
	s_nop 0
	v_addc_co_u32_e32 v41, vcc, 0, v1, vcc
	v_add_co_u32_e32 v42, vcc, s30, v0
	s_mov_b32 s31, 0xc0000
	s_nop 0
	v_addc_co_u32_e32 v43, vcc, 0, v1, vcc
	global_load_dword v30, v[20:21], off nt
	global_load_dword v31, v[22:23], off nt
	global_load_dword v32, v[24:25], off nt
	global_load_dword v33, v[26:27], off nt
	global_load_dword v34, v[28:29], off nt
	global_load_dword v35, v[38:39], off nt
	global_load_dword v36, v[40:41], off nt
	global_load_dword v37, v[42:43], off nt
	v_add_co_u32_e32 v20, vcc, s31, v0
	s_mov_b32 s33, 0xc8000
	s_nop 0
	v_addc_co_u32_e32 v21, vcc, 0, v1, vcc
	v_add_co_u32_e32 v22, vcc, s33, v0
	s_mov_b32 s38, 0xd0000
	s_nop 0
	v_addc_co_u32_e32 v23, vcc, 0, v1, vcc
	v_add_co_u32_e32 v24, vcc, s38, v0
	s_mov_b32 s39, 0xd8000
	s_nop 0
	v_addc_co_u32_e32 v25, vcc, 0, v1, vcc
	v_add_co_u32_e32 v26, vcc, s39, v0
	s_mov_b32 s8, 0xe0000
	s_nop 0
	v_addc_co_u32_e32 v27, vcc, 0, v1, vcc
	v_add_co_u32_e32 v28, vcc, s8, v0
	s_mov_b32 s8, 0xe8000
	s_nop 0
	v_addc_co_u32_e32 v29, vcc, 0, v1, vcc
	v_add_co_u32_e32 v46, vcc, s8, v0
	s_mov_b32 s8, 0xf0000
	s_nop 0
	v_addc_co_u32_e32 v47, vcc, 0, v1, vcc
	v_add_co_u32_e32 v48, vcc, s8, v0
	s_mov_b32 s8, 0xf8000
	s_nop 0
	v_addc_co_u32_e32 v49, vcc, 0, v1, vcc
	v_add_co_u32_e32 v0, vcc, s8, v0
	s_movk_i32 s8, 0x110
	s_nop 0
	v_addc_co_u32_e32 v1, vcc, 0, v1, vcc
	global_load_dword v38, v[20:21], off nt
	global_load_dword v39, v[22:23], off nt
	global_load_dword v40, v[24:25], off nt
	global_load_dword v41, v[26:27], off nt
	global_load_dword v42, v[28:29], off nt
	global_load_dword v43, v[46:47], off nt
	global_load_dword v44, v[48:49], off nt
	global_load_dword v45, v[0:1], off nt
	v_lshlrev_b32_e32 v0, 3, v50
	v_add_u32_e32 v22, 0x200, v50
	v_add_u32_e32 v24, 0x400, v50
	v_add_u32_e32 v26, 0x600, v50
	v_and_b32_e32 v0, 0x78, v0
	v_ashrrev_i32_e32 v20, 4, v50
	v_ashrrev_i32_e32 v22, 4, v22
	v_ashrrev_i32_e32 v24, 4, v24
	v_ashrrev_i32_e32 v26, 4, v26
	s_lshl_b32 s46, s42, 7
	s_mov_b32 s40, 0
	v_mov_b32_e32 v1, 0
	v_mul_lo_u32 v21, v20, s8
	v_mul_lo_u32 v23, v22, s8
	v_mul_lo_u32 v25, v24, s8
	v_mul_lo_u32 v27, v26, s8
	v_mul_u32_u24_e32 v28, 0x110, v2
	s_lshl_b32 s41, s96, 7
	v_add_u32_e32 v29, s46, v3
	s_movk_i32 s47, 0x7fff
	v_lshlrev_b32_e32 v0, 1, v0
	s_movk_i32 s48, 0x2c00
	s_mov_b32 s49, s96
	s_barrier
	s_branch .Lcvt2_1081

.Lcvt2_skip:
	s_add_u32 s3, s36, 0xe400000
	s_addc_u32 s33, s37, 0
	s_add_u32 s38, s36, 0x1bd3c000
	s_addc_u32 s39, s37, 0
	s_add_u32 s6, s36, 0x11400000
	s_addc_u32 s7, s37, 0
